# prompt-scan item prologue: 5 conv-weight loads issued together with one wait (plus the 64-bit state clear)
# baseline (speedup 1.0000x reference)
.LBB0_729:
	s_andn2_saveexec_b64 s[6:7], s[6:7]
	v_add_u32_e32 v0, s23, v144
	s_or_b64 exec, exec, s[6:7]
	v_ashrrev_i32_e32 v1, 31, v0
	v_lshlrev_b64 v[0:1], 2, v[0:1]
	v_lshl_add_u64 v[4:5], s[42:43], 0, v[0:1]
	v_readlane_b32 s6, v252, 47
	v_readlane_b32 s7, v252, 48
	global_load_dword v8, v[4:5], off
	v_add_co_u32_e32 v6, vcc, 0x4000, v4
	v_lshl_add_u32 v3, v144, 2, 0
	s_nop 0
	v_addc_co_u32_e32 v7, vcc, 0, v5, vcc
	global_load_dword v6, v[6:7], off
	v_add_co_u32_e32 v10, vcc, 0x8000, v4
	v_add_u32_e32 v3, 0x23000, v3
	s_nop 0
	v_addc_co_u32_e32 v11, vcc, 0, v5, vcc
	global_load_dword v10, v[10:11], off
	v_add_co_u32_e32 v12, vcc, 0xc000, v4
	v_lshl_add_u64 v[0:1], s[6:7], 0, v[0:1]
	s_nop 0
	v_addc_co_u32_e32 v13, vcc, 0, v5, vcc
	global_load_dword v12, v[12:13], off
	global_load_dword v0, v[0:1], off
	s_waitcnt vmcnt(0)
	ds_write2st64_b32 v3, v8, v6 offset1:5
	ds_write2st64_b32 v3, v10, v12 offset0:10 offset1:15
	ds_write_b32 v3, v0 offset:5120
